# GLA prep: gate vectors fetched with one vector load per 8 tokens and broadcast from a wave-private LDS slot (no per-token scalar-load latency)
# speedup vs baseline: 1.0131x; 1.0038x over previous
.LBB0_777:
	s_cmp_lt_i32 s90, 8
	s_cselect_b64 s[2:3], -1, 0
	s_add_u32 s36, s88, 0x115d000
	s_addc_u32 s37, s89, 0
	s_and_b64 s[18:19], s[2:3], s[0:1]
	s_andn2_b64 vcc, exec, s[18:19]
	s_cbranch_vccnz .LBB0_852
	s_cmpk_gt_i32 s58, 0x47f
	s_cbranch_scc1 .LBB0_851
	s_waitcnt vmcnt(0)
	v_readfirstlane_b32 s32, v0
	v_and_b32_e32 v2, 63, v0
	s_mov_b32 s33, 0xbfb8aa3b
	s_mov_b32 s35, 0x3f317217
	s_mov_b32 s36, 0x3377d1cf
	s_mov_b32 s37, 0x3d800000
	s_lshr_b32 s32, s32, 6
	v_lshlrev_b32_e32 v3, 3, v2
	v_lshlrev_b32_e32 v8, 1, v3
	v_lshlrev_b32_e32 v2, 2, v2
	s_lshl_b32 s92, s32, 10
	s_add_i32 s92, s92, 0x8000
	v_mov_b32_e32 v78, s92
	v_add_u32_e32 v9, s92, v8
	s_lshr_b32 s56, s58, 2
	s_mul_hi_u32 s57, s56, 0x71c71c8
	s_mul_i32 s34, s57, 108
	s_add_i32 s34, s34, s56
	s_and_b32 s57, s58, 3
	s_mul_i32 s57, s57, 36
	s_add_i32 s34, s34, s57
	s_mov_b32 s50, 0
	s_mul_hi_u32 s38, s34, 0x1c71c72
	s_mul_i32 s92, s38, 144
	s_sub_i32 s92, s34, s92
	s_mul_hi_u32 s40, s92, 0x71c71c8
	s_mul_i32 s93, s40, 36
	s_sub_i32 s39, s92, s93
	s_lshl_b32 s92, s38, 8
	s_lshl_b32 s93, s39, 6
	s_add_i32 s92, s92, s93
	s_addk_i32 s92, 0x4000
	s_lshl_b32 s94, s38, 11
	s_add_i32 s94, s94, s93
	s_addk_i32 s94, 0xff00
	s_cmp_lt_u32 s39, 4
	s_cselect_b32 s41, s92, s94
	s_lshl_b32 s92, s32, 3
	s_add_i32 s41, s41, s92
	s_lshl_b32 s95, s40, 8
	s_mul_i32 s92, s41, 0x1800
	s_add_u32 s92, s92, s95
	s_add_u32 s42, s96, s92
	s_addc_u32 s43, s97, 0
	s_lshl_b32 s92, s41, 10
	s_add_u32 s92, s92, s95
	s_add_u32 s44, s88, 0xa27d000
	s_addc_u32 s45, s89, 0
	s_add_u32 s44, s44, s92
	s_addc_u32 s45, s45, 0
	s_add_u32 s46, s44, 0x1000000
	s_addc_u32 s47, s45, 0
	s_lshl_b32 s92, s41, 7
	s_add_u32 s48, s88, 0xf1d000
	s_addc_u32 s49, s89, 0
	s_add_u32 s48, s48, s92
	s_addc_u32 s49, s49, 0
	s_lshl_b32 s95, s40, 9
	v_readlane_b32 s52, v251, 18
	v_readlane_b32 s53, v251, 19
	s_nop 3
	s_add_u32 s52, s52, s95
	s_addc_u32 s53, s53, 0
	global_load_dwordx2 v[10:11], v3, s[52:53]
	global_load_dwordx2 v[12:13], v3, s[52:53] offset:2048
	s_add_u32 s52, s52, 0x1000
	s_addc_u32 s53, s53, 0
	global_load_dwordx2 v[14:15], v3, s[52:53]
	global_load_dwordx2 v[16:17], v3, s[52:53] offset:2048
	s_add_u32 s52, s52, 0x1000
	s_addc_u32 s53, s53, 0
	global_load_dwordx2 v[18:19], v3, s[52:53]
	global_load_dwordx2 v[20:21], v3, s[52:53] offset:2048
	s_add_u32 s52, s52, 0x1000
	s_addc_u32 s53, s53, 0
	global_load_dwordx2 v[22:23], v3, s[52:53]
	global_load_dwordx2 v[24:25], v3, s[52:53] offset:2048
	s_add_u32 s52, s52, 0x1000
	s_addc_u32 s53, s53, 0
	global_load_dwordx2 v[26:27], v3, s[52:53]
	global_load_dwordx2 v[28:29], v3, s[52:53] offset:2048
	s_add_u32 s52, s52, 0x1000
	s_addc_u32 s53, s53, 0
	global_load_dwordx2 v[30:31], v3, s[52:53]
	global_load_dwordx2 v[32:33], v3, s[52:53] offset:2048
	s_add_u32 s52, s52, 0x1000
	s_addc_u32 s53, s53, 0
	global_load_dwordx2 v[34:35], v3, s[52:53]
	global_load_dwordx2 v[36:37], v3, s[52:53] offset:2048
	s_add_u32 s52, s52, 0x1000
	s_addc_u32 s53, s53, 0
	global_load_dwordx2 v[38:39], v3, s[52:53]
	global_load_dwordx2 v[40:41], v3, s[52:53] offset:2048
	v_readlane_b32 s52, v251, 24
	v_readlane_b32 s53, v251, 25
	s_nop 3
	s_add_u32 s52, s52, s95
	s_addc_u32 s53, s53, 0
	global_load_dwordx2 v[42:43], v3, s[52:53]
	global_load_dwordx2 v[44:45], v3, s[52:53] offset:2048
	s_add_u32 s52, s52, 0x1000
	s_addc_u32 s53, s53, 0
	global_load_dwordx2 v[46:47], v3, s[52:53]
	global_load_dwordx2 v[48:49], v3, s[52:53] offset:2048
	s_add_u32 s52, s52, 0x1000
	s_addc_u32 s53, s53, 0
	global_load_dwordx2 v[50:51], v3, s[52:53]
	global_load_dwordx2 v[52:53], v3, s[52:53] offset:2048
	s_add_u32 s52, s52, 0x1000
	s_addc_u32 s53, s53, 0
	global_load_dwordx2 v[54:55], v3, s[52:53]
	global_load_dwordx2 v[56:57], v3, s[52:53] offset:2048
	s_add_u32 s52, s52, 0x1000
	s_addc_u32 s53, s53, 0
	global_load_dwordx2 v[58:59], v3, s[52:53]
	global_load_dwordx2 v[60:61], v3, s[52:53] offset:2048
	s_add_u32 s52, s52, 0x1000
	s_addc_u32 s53, s53, 0
	global_load_dwordx2 v[62:63], v3, s[52:53]
	global_load_dwordx2 v[64:65], v3, s[52:53] offset:2048
	s_add_u32 s52, s52, 0x1000
	s_addc_u32 s53, s53, 0
	global_load_dwordx2 v[66:67], v3, s[52:53]
	global_load_dwordx2 v[68:69], v3, s[52:53] offset:2048
	s_add_u32 s52, s52, 0x1000
	s_addc_u32 s53, s53, 0
	global_load_dwordx2 v[70:71], v3, s[52:53]
	global_load_dwordx2 v[72:73], v3, s[52:53] offset:2048
	v_readlane_b32 s52, v251, 20
	v_readlane_b32 s53, v251, 21
	s_nop 3
	s_add_u32 s52, s52, s95
	s_addc_u32 s53, s53, 0
	global_load_dwordx2 v[74:75], v3, s[52:53]
	v_readlane_b32 s52, v251, 26
	v_readlane_b32 s53, v251, 27
	s_nop 3
	s_add_u32 s52, s52, s95
	s_addc_u32 s53, s53, 0
	global_load_dwordx2 v[76:77], v3, s[52:53]
	global_load_dwordx4 v[4:7], v8, s[48:49]
	s_mov_b64 s[52:53], s[42:43]
	global_load_dword v200, v2, s[52:53] offset:1024
	s_add_u32 s52, s52, 0x1800
	s_addc_u32 s53, s53, 0
	global_load_dword v201, v2, s[52:53] offset:1024
	s_add_u32 s52, s52, 0x1800
	s_addc_u32 s53, s53, 0
	global_load_dword v202, v2, s[52:53] offset:1024
	s_add_u32 s52, s52, 0x1800
	s_addc_u32 s53, s53, 0
	global_load_dword v203, v2, s[52:53] offset:1024
	s_add_u32 s52, s52, 0x1800
	s_addc_u32 s53, s53, 0
	global_load_dword v204, v2, s[52:53] offset:1024
	s_add_u32 s52, s52, 0x1800
	s_addc_u32 s53, s53, 0
	global_load_dword v205, v2, s[52:53] offset:1024
	s_add_u32 s52, s52, 0x1800
	s_addc_u32 s53, s53, 0
	global_load_dword v206, v2, s[52:53] offset:1024
	s_add_u32 s52, s52, 0x1800
	s_addc_u32 s53, s53, 0
	global_load_dword v207, v2, s[52:53] offset:1024
	s_cmp_lt_u32 s39, 4
	s_cbranch_scc1 .Lp7_noq_load_first
	s_mov_b64 s[52:53], s[42:43]
	global_load_dword v208, v2, s[52:53]
	s_add_u32 s52, s52, 0x1800
	s_addc_u32 s53, s53, 0
	global_load_dword v209, v2, s[52:53]
	s_add_u32 s52, s52, 0x1800
	s_addc_u32 s53, s53, 0
	global_load_dword v210, v2, s[52:53]
	s_add_u32 s52, s52, 0x1800
	s_addc_u32 s53, s53, 0
	global_load_dword v211, v2, s[52:53]
	s_add_u32 s52, s52, 0x1800
	s_addc_u32 s53, s53, 0
	global_load_dword v212, v2, s[52:53]
	s_add_u32 s52, s52, 0x1800
	s_addc_u32 s53, s53, 0
	global_load_dword v213, v2, s[52:53]
	s_add_u32 s52, s52, 0x1800
	s_addc_u32 s53, s53, 0
	global_load_dword v214, v2, s[52:53]
	s_add_u32 s52, s52, 0x1800
	s_addc_u32 s53, s53, 0
	global_load_dword v215, v2, s[52:53]

.Lp7_item:
	v_mov_b32_e32 v80, v200
	v_mov_b32_e32 v81, v201
	v_mov_b32_e32 v82, v202
	v_mov_b32_e32 v83, v203
	v_mov_b32_e32 v84, v204
	v_mov_b32_e32 v85, v205
	v_mov_b32_e32 v86, v206
	v_mov_b32_e32 v87, v207
	v_mov_b32_e32 v88, v208
	v_mov_b32_e32 v89, v209
	v_mov_b32_e32 v90, v210
	v_mov_b32_e32 v91, v211
	v_mov_b32_e32 v92, v212
	v_mov_b32_e32 v93, v213
	v_mov_b32_e32 v94, v214
	v_mov_b32_e32 v95, v215
	ds_write_b128 v9, v[4:7]
	ds_read_b128 v[216:219], v78 offset:0
	ds_read_b128 v[220:223], v78 offset:16
	ds_read_b128 v[224:227], v78 offset:32
	ds_read_b128 v[228:231], v78 offset:48
	ds_read_b128 v[232:235], v78 offset:64
	ds_read_b128 v[236:239], v78 offset:80
	ds_read_b128 v[240:243], v78 offset:96
	ds_read_b128 v[244:247], v78 offset:112
	s_waitcnt lgkmcnt(0)
	v_pk_fma_f32 v[128:129], v[10:11], v[216:217], v[74:75] op_sel_hi:[1,0,1]
	v_pk_fma_f32 v[128:129], v[12:13], v[216:217], v[128:129] op_sel:[0,1,0] op_sel_hi:[1,1,1]
	v_pk_fma_f32 v[128:129], v[14:15], v[218:219], v[128:129] op_sel_hi:[1,0,1]
	v_pk_fma_f32 v[128:129], v[16:17], v[218:219], v[128:129] op_sel:[0,1,0] op_sel_hi:[1,1,1]
	v_pk_fma_f32 v[128:129], v[18:19], v[220:221], v[128:129] op_sel_hi:[1,0,1]
	v_pk_fma_f32 v[128:129], v[20:21], v[220:221], v[128:129] op_sel:[0,1,0] op_sel_hi:[1,1,1]
	v_pk_fma_f32 v[128:129], v[22:23], v[222:223], v[128:129] op_sel_hi:[1,0,1]
	v_pk_fma_f32 v[128:129], v[24:25], v[222:223], v[128:129] op_sel:[0,1,0] op_sel_hi:[1,1,1]
	v_pk_fma_f32 v[128:129], v[26:27], v[224:225], v[128:129] op_sel_hi:[1,0,1]
	v_pk_fma_f32 v[128:129], v[28:29], v[224:225], v[128:129] op_sel:[0,1,0] op_sel_hi:[1,1,1]
	v_pk_fma_f32 v[128:129], v[30:31], v[226:227], v[128:129] op_sel_hi:[1,0,1]
	v_pk_fma_f32 v[128:129], v[32:33], v[226:227], v[128:129] op_sel:[0,1,0] op_sel_hi:[1,1,1]
	v_pk_fma_f32 v[128:129], v[34:35], v[228:229], v[128:129] op_sel_hi:[1,0,1]
	v_pk_fma_f32 v[128:129], v[36:37], v[228:229], v[128:129] op_sel:[0,1,0] op_sel_hi:[1,1,1]
	v_pk_fma_f32 v[128:129], v[38:39], v[230:231], v[128:129] op_sel_hi:[1,0,1]
	v_pk_fma_f32 v[128:129], v[40:41], v[230:231], v[128:129] op_sel:[0,1,0] op_sel_hi:[1,1,1]
	ds_read_b128 v[216:219], v78 offset:128
	ds_read_b128 v[220:223], v78 offset:144
	ds_read_b128 v[224:227], v78 offset:160
	ds_read_b128 v[228:231], v78 offset:176
	v_pk_fma_f32 v[130:131], v[42:43], v[232:233], v[76:77] op_sel_hi:[1,0,1]
	v_pk_fma_f32 v[130:131], v[44:45], v[232:233], v[130:131] op_sel:[0,1,0] op_sel_hi:[1,1,1]
	v_pk_fma_f32 v[130:131], v[46:47], v[234:235], v[130:131] op_sel_hi:[1,0,1]
	v_pk_fma_f32 v[130:131], v[48:49], v[234:235], v[130:131] op_sel:[0,1,0] op_sel_hi:[1,1,1]
	v_pk_fma_f32 v[130:131], v[50:51], v[236:237], v[130:131] op_sel_hi:[1,0,1]
	v_pk_fma_f32 v[130:131], v[52:53], v[236:237], v[130:131] op_sel:[0,1,0] op_sel_hi:[1,1,1]
	v_pk_fma_f32 v[130:131], v[54:55], v[238:239], v[130:131] op_sel_hi:[1,0,1]
	v_pk_fma_f32 v[130:131], v[56:57], v[238:239], v[130:131] op_sel:[0,1,0] op_sel_hi:[1,1,1]
	v_pk_fma_f32 v[130:131], v[58:59], v[240:241], v[130:131] op_sel_hi:[1,0,1]
	v_pk_fma_f32 v[130:131], v[60:61], v[240:241], v[130:131] op_sel:[0,1,0] op_sel_hi:[1,1,1]
	v_pk_fma_f32 v[130:131], v[62:63], v[242:243], v[130:131] op_sel_hi:[1,0,1]
	v_pk_fma_f32 v[130:131], v[64:65], v[242:243], v[130:131] op_sel:[0,1,0] op_sel_hi:[1,1,1]
	v_pk_fma_f32 v[130:131], v[66:67], v[244:245], v[130:131] op_sel_hi:[1,0,1]
	v_pk_fma_f32 v[130:131], v[68:69], v[244:245], v[130:131] op_sel:[0,1,0] op_sel_hi:[1,1,1]
	v_pk_fma_f32 v[130:131], v[70:71], v[246:247], v[130:131] op_sel_hi:[1,0,1]
	v_pk_fma_f32 v[130:131], v[72:73], v[246:247], v[130:131] op_sel:[0,1,0] op_sel_hi:[1,1,1]
	ds_read_b128 v[232:235], v78 offset:192
	ds_read_b128 v[236:239], v78 offset:208
	ds_read_b128 v[240:243], v78 offset:224
	ds_read_b128 v[244:247], v78 offset:240
	v_mul_f32_e64 v132, |v128|, s33
	v_mul_f32_e64 v133, |v129|, s33
	v_mul_f32_e64 v134, |v130|, s33
	v_mul_f32_e64 v135, |v131|, s33
	v_exp_f32_e32 v132, v132
	v_exp_f32_e32 v133, v133
	v_exp_f32_e32 v134, v134
	v_exp_f32_e32 v135, v135
	v_pk_add_f32 v[132:133], v[132:133], 1.0 op_sel_hi:[1,0]
	v_pk_add_f32 v[134:135], v[134:135], 1.0 op_sel_hi:[1,0]
	v_log_f32_e32 v136, v132
	v_log_f32_e32 v137, v133
	v_log_f32_e32 v138, v134
	v_log_f32_e32 v139, v135
	v_pk_mul_f32 v[140:141], v[136:137], s[34:35] op_sel:[0,1] op_sel_hi:[1,1]
	v_pk_mul_f32 v[142:143], v[138:139], s[34:35] op_sel:[0,1] op_sel_hi:[1,1]
	v_pk_fma_f32 v[144:145], v[136:137], s[34:35], v[140:141] op_sel:[0,1,0] op_sel_hi:[1,1,1] neg_lo:[0,0,1] neg_hi:[0,0,1]
	v_pk_fma_f32 v[146:147], v[138:139], s[34:35], v[142:143] op_sel:[0,1,0] op_sel_hi:[1,1,1] neg_lo:[0,0,1] neg_hi:[0,0,1]
	v_pk_fma_f32 v[144:145], v[136:137], s[36:37], v[144:145] op_sel_hi:[1,0,1]
	v_pk_fma_f32 v[146:147], v[138:139], s[36:37], v[146:147] op_sel_hi:[1,0,1]
	v_pk_fma_f32 v[144:145], v[136:137], s[34:35], v[144:145] op_sel:[0,1,0] op_sel_hi:[1,1,1]
	v_pk_fma_f32 v[146:147], v[138:139], s[34:35], v[146:147] op_sel:[0,1,0] op_sel_hi:[1,1,1]
	v_min_f32_e32 v128, 0, v128
	v_min_f32_e32 v129, 0, v129
	v_min_f32_e32 v130, 0, v130
	v_min_f32_e32 v131, 0, v131
	v_pk_add_f32 v[128:129], v[128:129], v[144:145] neg_lo:[0,1] neg_hi:[0,1]
	v_pk_add_f32 v[130:131], v[130:131], v[146:147] neg_lo:[0,1] neg_hi:[0,1]
	v_pk_mul_f32 v[96:97], v[128:129], s[36:37] op_sel:[0,1] op_sel_hi:[1,1]
	v_pk_mul_f32 v[112:113], v[130:131], s[36:37] op_sel:[0,1] op_sel_hi:[1,1]
	s_waitcnt lgkmcnt(0)
	v_pk_fma_f32 v[128:129], v[10:11], v[216:217], v[74:75] op_sel_hi:[1,0,1]
	v_pk_fma_f32 v[128:129], v[12:13], v[216:217], v[128:129] op_sel:[0,1,0] op_sel_hi:[1,1,1]
	v_pk_fma_f32 v[128:129], v[14:15], v[218:219], v[128:129] op_sel_hi:[1,0,1]
	v_pk_fma_f32 v[128:129], v[16:17], v[218:219], v[128:129] op_sel:[0,1,0] op_sel_hi:[1,1,1]
	v_pk_fma_f32 v[128:129], v[18:19], v[220:221], v[128:129] op_sel_hi:[1,0,1]
	v_pk_fma_f32 v[128:129], v[20:21], v[220:221], v[128:129] op_sel:[0,1,0] op_sel_hi:[1,1,1]
	v_pk_fma_f32 v[128:129], v[22:23], v[222:223], v[128:129] op_sel_hi:[1,0,1]
	v_pk_fma_f32 v[128:129], v[24:25], v[222:223], v[128:129] op_sel:[0,1,0] op_sel_hi:[1,1,1]
	v_pk_fma_f32 v[128:129], v[26:27], v[224:225], v[128:129] op_sel_hi:[1,0,1]
	v_pk_fma_f32 v[128:129], v[28:29], v[224:225], v[128:129] op_sel:[0,1,0] op_sel_hi:[1,1,1]
	v_pk_fma_f32 v[128:129], v[30:31], v[226:227], v[128:129] op_sel_hi:[1,0,1]
	v_pk_fma_f32 v[128:129], v[32:33], v[226:227], v[128:129] op_sel:[0,1,0] op_sel_hi:[1,1,1]
	v_pk_fma_f32 v[128:129], v[34:35], v[228:229], v[128:129] op_sel_hi:[1,0,1]
	v_pk_fma_f32 v[128:129], v[36:37], v[228:229], v[128:129] op_sel:[0,1,0] op_sel_hi:[1,1,1]
	v_pk_fma_f32 v[128:129], v[38:39], v[230:231], v[128:129] op_sel_hi:[1,0,1]
	v_pk_fma_f32 v[128:129], v[40:41], v[230:231], v[128:129] op_sel:[0,1,0] op_sel_hi:[1,1,1]
	ds_read_b128 v[216:219], v78 offset:256
	ds_read_b128 v[220:223], v78 offset:272
	ds_read_b128 v[224:227], v78 offset:288
	ds_read_b128 v[228:231], v78 offset:304
	v_pk_fma_f32 v[130:131], v[42:43], v[232:233], v[76:77] op_sel_hi:[1,0,1]
	v_pk_fma_f32 v[130:131], v[44:45], v[232:233], v[130:131] op_sel:[0,1,0] op_sel_hi:[1,1,1]
	v_pk_fma_f32 v[130:131], v[46:47], v[234:235], v[130:131] op_sel_hi:[1,0,1]
	v_pk_fma_f32 v[130:131], v[48:49], v[234:235], v[130:131] op_sel:[0,1,0] op_sel_hi:[1,1,1]
	v_pk_fma_f32 v[130:131], v[50:51], v[236:237], v[130:131] op_sel_hi:[1,0,1]
	v_pk_fma_f32 v[130:131], v[52:53], v[236:237], v[130:131] op_sel:[0,1,0] op_sel_hi:[1,1,1]
	v_pk_fma_f32 v[130:131], v[54:55], v[238:239], v[130:131] op_sel_hi:[1,0,1]
	v_pk_fma_f32 v[130:131], v[56:57], v[238:239], v[130:131] op_sel:[0,1,0] op_sel_hi:[1,1,1]
	v_pk_fma_f32 v[130:131], v[58:59], v[240:241], v[130:131] op_sel_hi:[1,0,1]
	v_pk_fma_f32 v[130:131], v[60:61], v[240:241], v[130:131] op_sel:[0,1,0] op_sel_hi:[1,1,1]
	v_pk_fma_f32 v[130:131], v[62:63], v[242:243], v[130:131] op_sel_hi:[1,0,1]
	v_pk_fma_f32 v[130:131], v[64:65], v[242:243], v[130:131] op_sel:[0,1,0] op_sel_hi:[1,1,1]
	v_pk_fma_f32 v[130:131], v[66:67], v[244:245], v[130:131] op_sel_hi:[1,0,1]
	v_pk_fma_f32 v[130:131], v[68:69], v[244:245], v[130:131] op_sel:[0,1,0] op_sel_hi:[1,1,1]
	v_pk_fma_f32 v[130:131], v[70:71], v[246:247], v[130:131] op_sel_hi:[1,0,1]
	v_pk_fma_f32 v[130:131], v[72:73], v[246:247], v[130:131] op_sel:[0,1,0] op_sel_hi:[1,1,1]
	ds_read_b128 v[232:235], v78 offset:320
	ds_read_b128 v[236:239], v78 offset:336
	ds_read_b128 v[240:243], v78 offset:352
	ds_read_b128 v[244:247], v78 offset:368
	v_mul_f32_e64 v132, |v128|, s33
	v_mul_f32_e64 v133, |v129|, s33
	v_mul_f32_e64 v134, |v130|, s33
	v_mul_f32_e64 v135, |v131|, s33
	v_exp_f32_e32 v132, v132
	v_exp_f32_e32 v133, v133
	v_exp_f32_e32 v134, v134
	v_exp_f32_e32 v135, v135
	v_pk_add_f32 v[132:133], v[132:133], 1.0 op_sel_hi:[1,0]
	v_pk_add_f32 v[134:135], v[134:135], 1.0 op_sel_hi:[1,0]
	v_log_f32_e32 v136, v132
	v_log_f32_e32 v137, v133
	v_log_f32_e32 v138, v134
	v_log_f32_e32 v139, v135
	v_pk_mul_f32 v[140:141], v[136:137], s[34:35] op_sel:[0,1] op_sel_hi:[1,1]
	v_pk_mul_f32 v[142:143], v[138:139], s[34:35] op_sel:[0,1] op_sel_hi:[1,1]
	v_pk_fma_f32 v[144:145], v[136:137], s[34:35], v[140:141] op_sel:[0,1,0] op_sel_hi:[1,1,1] neg_lo:[0,0,1] neg_hi:[0,0,1]
	v_pk_fma_f32 v[146:147], v[138:139], s[34:35], v[142:143] op_sel:[0,1,0] op_sel_hi:[1,1,1] neg_lo:[0,0,1] neg_hi:[0,0,1]
	v_pk_fma_f32 v[144:145], v[136:137], s[36:37], v[144:145] op_sel_hi:[1,0,1]
	v_pk_fma_f32 v[146:147], v[138:139], s[36:37], v[146:147] op_sel_hi:[1,0,1]
	v_pk_fma_f32 v[144:145], v[136:137], s[34:35], v[144:145] op_sel:[0,1,0] op_sel_hi:[1,1,1]
	v_pk_fma_f32 v[146:147], v[138:139], s[34:35], v[146:147] op_sel:[0,1,0] op_sel_hi:[1,1,1]
	v_min_f32_e32 v128, 0, v128
	v_min_f32_e32 v129, 0, v129
	v_min_f32_e32 v130, 0, v130
	v_min_f32_e32 v131, 0, v131
	v_pk_add_f32 v[128:129], v[128:129], v[144:145] neg_lo:[0,1] neg_hi:[0,1]
	v_pk_add_f32 v[130:131], v[130:131], v[146:147] neg_lo:[0,1] neg_hi:[0,1]
	v_pk_mul_f32 v[98:99], v[128:129], s[36:37] op_sel:[0,1] op_sel_hi:[1,1]
	v_pk_mul_f32 v[114:115], v[130:131], s[36:37] op_sel:[0,1] op_sel_hi:[1,1]
	s_waitcnt lgkmcnt(0)
	v_pk_fma_f32 v[128:129], v[10:11], v[216:217], v[74:75] op_sel_hi:[1,0,1]
	v_pk_fma_f32 v[128:129], v[12:13], v[216:217], v[128:129] op_sel:[0,1,0] op_sel_hi:[1,1,1]
	v_pk_fma_f32 v[128:129], v[14:15], v[218:219], v[128:129] op_sel_hi:[1,0,1]
	v_pk_fma_f32 v[128:129], v[16:17], v[218:219], v[128:129] op_sel:[0,1,0] op_sel_hi:[1,1,1]
	v_pk_fma_f32 v[128:129], v[18:19], v[220:221], v[128:129] op_sel_hi:[1,0,1]
	v_pk_fma_f32 v[128:129], v[20:21], v[220:221], v[128:129] op_sel:[0,1,0] op_sel_hi:[1,1,1]
	v_pk_fma_f32 v[128:129], v[22:23], v[222:223], v[128:129] op_sel_hi:[1,0,1]
	v_pk_fma_f32 v[128:129], v[24:25], v[222:223], v[128:129] op_sel:[0,1,0] op_sel_hi:[1,1,1]
	v_pk_fma_f32 v[128:129], v[26:27], v[224:225], v[128:129] op_sel_hi:[1,0,1]
	v_pk_fma_f32 v[128:129], v[28:29], v[224:225], v[128:129] op_sel:[0,1,0] op_sel_hi:[1,1,1]
	v_pk_fma_f32 v[128:129], v[30:31], v[226:227], v[128:129] op_sel_hi:[1,0,1]
	v_pk_fma_f32 v[128:129], v[32:33], v[226:227], v[128:129] op_sel:[0,1,0] op_sel_hi:[1,1,1]
	v_pk_fma_f32 v[128:129], v[34:35], v[228:229], v[128:129] op_sel_hi:[1,0,1]
	v_pk_fma_f32 v[128:129], v[36:37], v[228:229], v[128:129] op_sel:[0,1,0] op_sel_hi:[1,1,1]
	v_pk_fma_f32 v[128:129], v[38:39], v[230:231], v[128:129] op_sel_hi:[1,0,1]
	v_pk_fma_f32 v[128:129], v[40:41], v[230:231], v[128:129] op_sel:[0,1,0] op_sel_hi:[1,1,1]
	ds_read_b128 v[216:219], v78 offset:384
	ds_read_b128 v[220:223], v78 offset:400
	ds_read_b128 v[224:227], v78 offset:416
	ds_read_b128 v[228:231], v78 offset:432
	v_pk_fma_f32 v[130:131], v[42:43], v[232:233], v[76:77] op_sel_hi:[1,0,1]
	v_pk_fma_f32 v[130:131], v[44:45], v[232:233], v[130:131] op_sel:[0,1,0] op_sel_hi:[1,1,1]
	v_pk_fma_f32 v[130:131], v[46:47], v[234:235], v[130:131] op_sel_hi:[1,0,1]
	v_pk_fma_f32 v[130:131], v[48:49], v[234:235], v[130:131] op_sel:[0,1,0] op_sel_hi:[1,1,1]
	v_pk_fma_f32 v[130:131], v[50:51], v[236:237], v[130:131] op_sel_hi:[1,0,1]
	v_pk_fma_f32 v[130:131], v[52:53], v[236:237], v[130:131] op_sel:[0,1,0] op_sel_hi:[1,1,1]
	v_pk_fma_f32 v[130:131], v[54:55], v[238:239], v[130:131] op_sel_hi:[1,0,1]
	v_pk_fma_f32 v[130:131], v[56:57], v[238:239], v[130:131] op_sel:[0,1,0] op_sel_hi:[1,1,1]
	v_pk_fma_f32 v[130:131], v[58:59], v[240:241], v[130:131] op_sel_hi:[1,0,1]
	v_pk_fma_f32 v[130:131], v[60:61], v[240:241], v[130:131] op_sel:[0,1,0] op_sel_hi:[1,1,1]
	v_pk_fma_f32 v[130:131], v[62:63], v[242:243], v[130:131] op_sel_hi:[1,0,1]
	v_pk_fma_f32 v[130:131], v[64:65], v[242:243], v[130:131] op_sel:[0,1,0] op_sel_hi:[1,1,1]
	v_pk_fma_f32 v[130:131], v[66:67], v[244:245], v[130:131] op_sel_hi:[1,0,1]
	v_pk_fma_f32 v[130:131], v[68:69], v[244:245], v[130:131] op_sel:[0,1,0] op_sel_hi:[1,1,1]
	v_pk_fma_f32 v[130:131], v[70:71], v[246:247], v[130:131] op_sel_hi:[1,0,1]
	v_pk_fma_f32 v[130:131], v[72:73], v[246:247], v[130:131] op_sel:[0,1,0] op_sel_hi:[1,1,1]
	ds_read_b128 v[232:235], v78 offset:448
	ds_read_b128 v[236:239], v78 offset:464
	ds_read_b128 v[240:243], v78 offset:480
	ds_read_b128 v[244:247], v78 offset:496
	v_mul_f32_e64 v132, |v128|, s33
	v_mul_f32_e64 v133, |v129|, s33
	v_mul_f32_e64 v134, |v130|, s33
	v_mul_f32_e64 v135, |v131|, s33
	v_exp_f32_e32 v132, v132
	v_exp_f32_e32 v133, v133
	v_exp_f32_e32 v134, v134
	v_exp_f32_e32 v135, v135
	v_pk_add_f32 v[132:133], v[132:133], 1.0 op_sel_hi:[1,0]
	v_pk_add_f32 v[134:135], v[134:135], 1.0 op_sel_hi:[1,0]
	v_log_f32_e32 v136, v132
	v_log_f32_e32 v137, v133
	v_log_f32_e32 v138, v134
	v_log_f32_e32 v139, v135
	v_pk_mul_f32 v[140:141], v[136:137], s[34:35] op_sel:[0,1] op_sel_hi:[1,1]
	v_pk_mul_f32 v[142:143], v[138:139], s[34:35] op_sel:[0,1] op_sel_hi:[1,1]
	v_pk_fma_f32 v[144:145], v[136:137], s[34:35], v[140:141] op_sel:[0,1,0] op_sel_hi:[1,1,1] neg_lo:[0,0,1] neg_hi:[0,0,1]
	v_pk_fma_f32 v[146:147], v[138:139], s[34:35], v[142:143] op_sel:[0,1,0] op_sel_hi:[1,1,1] neg_lo:[0,0,1] neg_hi:[0,0,1]
	v_pk_fma_f32 v[144:145], v[136:137], s[36:37], v[144:145] op_sel_hi:[1,0,1]
	v_pk_fma_f32 v[146:147], v[138:139], s[36:37], v[146:147] op_sel_hi:[1,0,1]
	v_pk_fma_f32 v[144:145], v[136:137], s[34:35], v[144:145] op_sel:[0,1,0] op_sel_hi:[1,1,1]
	v_pk_fma_f32 v[146:147], v[138:139], s[34:35], v[146:147] op_sel:[0,1,0] op_sel_hi:[1,1,1]
	v_min_f32_e32 v128, 0, v128
	v_min_f32_e32 v129, 0, v129
	v_min_f32_e32 v130, 0, v130
	v_min_f32_e32 v131, 0, v131
	v_pk_add_f32 v[128:129], v[128:129], v[144:145] neg_lo:[0,1] neg_hi:[0,1]
	v_pk_add_f32 v[130:131], v[130:131], v[146:147] neg_lo:[0,1] neg_hi:[0,1]
	v_pk_mul_f32 v[100:101], v[128:129], s[36:37] op_sel:[0,1] op_sel_hi:[1,1]
	v_pk_mul_f32 v[116:117], v[130:131], s[36:37] op_sel:[0,1] op_sel_hi:[1,1]
	s_waitcnt lgkmcnt(0)
	v_pk_fma_f32 v[128:129], v[10:11], v[216:217], v[74:75] op_sel_hi:[1,0,1]
	v_pk_fma_f32 v[128:129], v[12:13], v[216:217], v[128:129] op_sel:[0,1,0] op_sel_hi:[1,1,1]
	v_pk_fma_f32 v[128:129], v[14:15], v[218:219], v[128:129] op_sel_hi:[1,0,1]
	v_pk_fma_f32 v[128:129], v[16:17], v[218:219], v[128:129] op_sel:[0,1,0] op_sel_hi:[1,1,1]
	v_pk_fma_f32 v[128:129], v[18:19], v[220:221], v[128:129] op_sel_hi:[1,0,1]
	v_pk_fma_f32 v[128:129], v[20:21], v[220:221], v[128:129] op_sel:[0,1,0] op_sel_hi:[1,1,1]
	v_pk_fma_f32 v[128:129], v[22:23], v[222:223], v[128:129] op_sel_hi:[1,0,1]
	v_pk_fma_f32 v[128:129], v[24:25], v[222:223], v[128:129] op_sel:[0,1,0] op_sel_hi:[1,1,1]
	v_pk_fma_f32 v[128:129], v[26:27], v[224:225], v[128:129] op_sel_hi:[1,0,1]
	v_pk_fma_f32 v[128:129], v[28:29], v[224:225], v[128:129] op_sel:[0,1,0] op_sel_hi:[1,1,1]
	v_pk_fma_f32 v[128:129], v[30:31], v[226:227], v[128:129] op_sel_hi:[1,0,1]
	v_pk_fma_f32 v[128:129], v[32:33], v[226:227], v[128:129] op_sel:[0,1,0] op_sel_hi:[1,1,1]
	v_pk_fma_f32 v[128:129], v[34:35], v[228:229], v[128:129] op_sel_hi:[1,0,1]
	v_pk_fma_f32 v[128:129], v[36:37], v[228:229], v[128:129] op_sel:[0,1,0] op_sel_hi:[1,1,1]
	v_pk_fma_f32 v[128:129], v[38:39], v[230:231], v[128:129] op_sel_hi:[1,0,1]
	v_pk_fma_f32 v[128:129], v[40:41], v[230:231], v[128:129] op_sel:[0,1,0] op_sel_hi:[1,1,1]
	ds_read_b128 v[216:219], v78 offset:512
	ds_read_b128 v[220:223], v78 offset:528
	ds_read_b128 v[224:227], v78 offset:544
	ds_read_b128 v[228:231], v78 offset:560
	v_pk_fma_f32 v[130:131], v[42:43], v[232:233], v[76:77] op_sel_hi:[1,0,1]
	v_pk_fma_f32 v[130:131], v[44:45], v[232:233], v[130:131] op_sel:[0,1,0] op_sel_hi:[1,1,1]
	v_pk_fma_f32 v[130:131], v[46:47], v[234:235], v[130:131] op_sel_hi:[1,0,1]
	v_pk_fma_f32 v[130:131], v[48:49], v[234:235], v[130:131] op_sel:[0,1,0] op_sel_hi:[1,1,1]
	v_pk_fma_f32 v[130:131], v[50:51], v[236:237], v[130:131] op_sel_hi:[1,0,1]
	v_pk_fma_f32 v[130:131], v[52:53], v[236:237], v[130:131] op_sel:[0,1,0] op_sel_hi:[1,1,1]
	v_pk_fma_f32 v[130:131], v[54:55], v[238:239], v[130:131] op_sel_hi:[1,0,1]
	v_pk_fma_f32 v[130:131], v[56:57], v[238:239], v[130:131] op_sel:[0,1,0] op_sel_hi:[1,1,1]
	v_pk_fma_f32 v[130:131], v[58:59], v[240:241], v[130:131] op_sel_hi:[1,0,1]
	v_pk_fma_f32 v[130:131], v[60:61], v[240:241], v[130:131] op_sel:[0,1,0] op_sel_hi:[1,1,1]
	v_pk_fma_f32 v[130:131], v[62:63], v[242:243], v[130:131] op_sel_hi:[1,0,1]
	v_pk_fma_f32 v[130:131], v[64:65], v[242:243], v[130:131] op_sel:[0,1,0] op_sel_hi:[1,1,1]
	v_pk_fma_f32 v[130:131], v[66:67], v[244:245], v[130:131] op_sel_hi:[1,0,1]
	v_pk_fma_f32 v[130:131], v[68:69], v[244:245], v[130:131] op_sel:[0,1,0] op_sel_hi:[1,1,1]
	v_pk_fma_f32 v[130:131], v[70:71], v[246:247], v[130:131] op_sel_hi:[1,0,1]
	v_pk_fma_f32 v[130:131], v[72:73], v[246:247], v[130:131] op_sel:[0,1,0] op_sel_hi:[1,1,1]
	ds_read_b128 v[232:235], v78 offset:576
	ds_read_b128 v[236:239], v78 offset:592
	ds_read_b128 v[240:243], v78 offset:608
	ds_read_b128 v[244:247], v78 offset:624
	v_mul_f32_e64 v132, |v128|, s33
	v_mul_f32_e64 v133, |v129|, s33
	v_mul_f32_e64 v134, |v130|, s33
	v_mul_f32_e64 v135, |v131|, s33
	v_exp_f32_e32 v132, v132
	v_exp_f32_e32 v133, v133
	v_exp_f32_e32 v134, v134
	v_exp_f32_e32 v135, v135
	v_pk_add_f32 v[132:133], v[132:133], 1.0 op_sel_hi:[1,0]
	v_pk_add_f32 v[134:135], v[134:135], 1.0 op_sel_hi:[1,0]
	v_log_f32_e32 v136, v132
	v_log_f32_e32 v137, v133
	v_log_f32_e32 v138, v134
	v_log_f32_e32 v139, v135
	v_pk_mul_f32 v[140:141], v[136:137], s[34:35] op_sel:[0,1] op_sel_hi:[1,1]
	v_pk_mul_f32 v[142:143], v[138:139], s[34:35] op_sel:[0,1] op_sel_hi:[1,1]
	v_pk_fma_f32 v[144:145], v[136:137], s[34:35], v[140:141] op_sel:[0,1,0] op_sel_hi:[1,1,1] neg_lo:[0,0,1] neg_hi:[0,0,1]
	v_pk_fma_f32 v[146:147], v[138:139], s[34:35], v[142:143] op_sel:[0,1,0] op_sel_hi:[1,1,1] neg_lo:[0,0,1] neg_hi:[0,0,1]
	v_pk_fma_f32 v[144:145], v[136:137], s[36:37], v[144:145] op_sel_hi:[1,0,1]
	v_pk_fma_f32 v[146:147], v[138:139], s[36:37], v[146:147] op_sel_hi:[1,0,1]
	v_pk_fma_f32 v[144:145], v[136:137], s[34:35], v[144:145] op_sel:[0,1,0] op_sel_hi:[1,1,1]
	v_pk_fma_f32 v[146:147], v[138:139], s[34:35], v[146:147] op_sel:[0,1,0] op_sel_hi:[1,1,1]
	v_min_f32_e32 v128, 0, v128
	v_min_f32_e32 v129, 0, v129
	v_min_f32_e32 v130, 0, v130
	v_min_f32_e32 v131, 0, v131
	v_pk_add_f32 v[128:129], v[128:129], v[144:145] neg_lo:[0,1] neg_hi:[0,1]
	v_pk_add_f32 v[130:131], v[130:131], v[146:147] neg_lo:[0,1] neg_hi:[0,1]
	v_pk_mul_f32 v[102:103], v[128:129], s[36:37] op_sel:[0,1] op_sel_hi:[1,1]
	v_pk_mul_f32 v[118:119], v[130:131], s[36:37] op_sel:[0,1] op_sel_hi:[1,1]
	s_waitcnt lgkmcnt(0)
	v_pk_fma_f32 v[128:129], v[10:11], v[216:217], v[74:75] op_sel_hi:[1,0,1]
	v_pk_fma_f32 v[128:129], v[12:13], v[216:217], v[128:129] op_sel:[0,1,0] op_sel_hi:[1,1,1]
	v_pk_fma_f32 v[128:129], v[14:15], v[218:219], v[128:129] op_sel_hi:[1,0,1]
	v_pk_fma_f32 v[128:129], v[16:17], v[218:219], v[128:129] op_sel:[0,1,0] op_sel_hi:[1,1,1]
	v_pk_fma_f32 v[128:129], v[18:19], v[220:221], v[128:129] op_sel_hi:[1,0,1]
	v_pk_fma_f32 v[128:129], v[20:21], v[220:221], v[128:129] op_sel:[0,1,0] op_sel_hi:[1,1,1]
	v_pk_fma_f32 v[128:129], v[22:23], v[222:223], v[128:129] op_sel_hi:[1,0,1]
	v_pk_fma_f32 v[128:129], v[24:25], v[222:223], v[128:129] op_sel:[0,1,0] op_sel_hi:[1,1,1]
	v_pk_fma_f32 v[128:129], v[26:27], v[224:225], v[128:129] op_sel_hi:[1,0,1]
	v_pk_fma_f32 v[128:129], v[28:29], v[224:225], v[128:129] op_sel:[0,1,0] op_sel_hi:[1,1,1]
	v_pk_fma_f32 v[128:129], v[30:31], v[226:227], v[128:129] op_sel_hi:[1,0,1]
	v_pk_fma_f32 v[128:129], v[32:33], v[226:227], v[128:129] op_sel:[0,1,0] op_sel_hi:[1,1,1]
	v_pk_fma_f32 v[128:129], v[34:35], v[228:229], v[128:129] op_sel_hi:[1,0,1]
	v_pk_fma_f32 v[128:129], v[36:37], v[228:229], v[128:129] op_sel:[0,1,0] op_sel_hi:[1,1,1]
	v_pk_fma_f32 v[128:129], v[38:39], v[230:231], v[128:129] op_sel_hi:[1,0,1]
	v_pk_fma_f32 v[128:129], v[40:41], v[230:231], v[128:129] op_sel:[0,1,0] op_sel_hi:[1,1,1]
	ds_read_b128 v[216:219], v78 offset:640
	ds_read_b128 v[220:223], v78 offset:656
	ds_read_b128 v[224:227], v78 offset:672
	ds_read_b128 v[228:231], v78 offset:688
	v_pk_fma_f32 v[130:131], v[42:43], v[232:233], v[76:77] op_sel_hi:[1,0,1]
	v_pk_fma_f32 v[130:131], v[44:45], v[232:233], v[130:131] op_sel:[0,1,0] op_sel_hi:[1,1,1]
	v_pk_fma_f32 v[130:131], v[46:47], v[234:235], v[130:131] op_sel_hi:[1,0,1]
	v_pk_fma_f32 v[130:131], v[48:49], v[234:235], v[130:131] op_sel:[0,1,0] op_sel_hi:[1,1,1]
	v_pk_fma_f32 v[130:131], v[50:51], v[236:237], v[130:131] op_sel_hi:[1,0,1]
	v_pk_fma_f32 v[130:131], v[52:53], v[236:237], v[130:131] op_sel:[0,1,0] op_sel_hi:[1,1,1]
	v_pk_fma_f32 v[130:131], v[54:55], v[238:239], v[130:131] op_sel_hi:[1,0,1]
	v_pk_fma_f32 v[130:131], v[56:57], v[238:239], v[130:131] op_sel:[0,1,0] op_sel_hi:[1,1,1]
	v_pk_fma_f32 v[130:131], v[58:59], v[240:241], v[130:131] op_sel_hi:[1,0,1]
	v_pk_fma_f32 v[130:131], v[60:61], v[240:241], v[130:131] op_sel:[0,1,0] op_sel_hi:[1,1,1]
	v_pk_fma_f32 v[130:131], v[62:63], v[242:243], v[130:131] op_sel_hi:[1,0,1]
	v_pk_fma_f32 v[130:131], v[64:65], v[242:243], v[130:131] op_sel:[0,1,0] op_sel_hi:[1,1,1]
	v_pk_fma_f32 v[130:131], v[66:67], v[244:245], v[130:131] op_sel_hi:[1,0,1]
	v_pk_fma_f32 v[130:131], v[68:69], v[244:245], v[130:131] op_sel:[0,1,0] op_sel_hi:[1,1,1]
	v_pk_fma_f32 v[130:131], v[70:71], v[246:247], v[130:131] op_sel_hi:[1,0,1]
	v_pk_fma_f32 v[130:131], v[72:73], v[246:247], v[130:131] op_sel:[0,1,0] op_sel_hi:[1,1,1]
	ds_read_b128 v[232:235], v78 offset:704
	ds_read_b128 v[236:239], v78 offset:720
	ds_read_b128 v[240:243], v78 offset:736
	ds_read_b128 v[244:247], v78 offset:752
	v_mul_f32_e64 v132, |v128|, s33
	v_mul_f32_e64 v133, |v129|, s33
	v_mul_f32_e64 v134, |v130|, s33
	v_mul_f32_e64 v135, |v131|, s33
	v_exp_f32_e32 v132, v132
	v_exp_f32_e32 v133, v133
	v_exp_f32_e32 v134, v134
	v_exp_f32_e32 v135, v135
	v_pk_add_f32 v[132:133], v[132:133], 1.0 op_sel_hi:[1,0]
	v_pk_add_f32 v[134:135], v[134:135], 1.0 op_sel_hi:[1,0]
	v_log_f32_e32 v136, v132
	v_log_f32_e32 v137, v133
	v_log_f32_e32 v138, v134
	v_log_f32_e32 v139, v135
	v_pk_mul_f32 v[140:141], v[136:137], s[34:35] op_sel:[0,1] op_sel_hi:[1,1]
	v_pk_mul_f32 v[142:143], v[138:139], s[34:35] op_sel:[0,1] op_sel_hi:[1,1]
	v_pk_fma_f32 v[144:145], v[136:137], s[34:35], v[140:141] op_sel:[0,1,0] op_sel_hi:[1,1,1] neg_lo:[0,0,1] neg_hi:[0,0,1]
	v_pk_fma_f32 v[146:147], v[138:139], s[34:35], v[142:143] op_sel:[0,1,0] op_sel_hi:[1,1,1] neg_lo:[0,0,1] neg_hi:[0,0,1]
	v_pk_fma_f32 v[144:145], v[136:137], s[36:37], v[144:145] op_sel_hi:[1,0,1]
	v_pk_fma_f32 v[146:147], v[138:139], s[36:37], v[146:147] op_sel_hi:[1,0,1]
	v_pk_fma_f32 v[144:145], v[136:137], s[34:35], v[144:145] op_sel:[0,1,0] op_sel_hi:[1,1,1]
	v_pk_fma_f32 v[146:147], v[138:139], s[34:35], v[146:147] op_sel:[0,1,0] op_sel_hi:[1,1,1]
	v_min_f32_e32 v128, 0, v128
	v_min_f32_e32 v129, 0, v129
	v_min_f32_e32 v130, 0, v130
	v_min_f32_e32 v131, 0, v131
	v_pk_add_f32 v[128:129], v[128:129], v[144:145] neg_lo:[0,1] neg_hi:[0,1]
	v_pk_add_f32 v[130:131], v[130:131], v[146:147] neg_lo:[0,1] neg_hi:[0,1]
	v_pk_mul_f32 v[104:105], v[128:129], s[36:37] op_sel:[0,1] op_sel_hi:[1,1]
	v_pk_mul_f32 v[120:121], v[130:131], s[36:37] op_sel:[0,1] op_sel_hi:[1,1]
	s_waitcnt lgkmcnt(0)
	v_pk_fma_f32 v[128:129], v[10:11], v[216:217], v[74:75] op_sel_hi:[1,0,1]
	v_pk_fma_f32 v[128:129], v[12:13], v[216:217], v[128:129] op_sel:[0,1,0] op_sel_hi:[1,1,1]
	v_pk_fma_f32 v[128:129], v[14:15], v[218:219], v[128:129] op_sel_hi:[1,0,1]
	v_pk_fma_f32 v[128:129], v[16:17], v[218:219], v[128:129] op_sel:[0,1,0] op_sel_hi:[1,1,1]
	v_pk_fma_f32 v[128:129], v[18:19], v[220:221], v[128:129] op_sel_hi:[1,0,1]
	v_pk_fma_f32 v[128:129], v[20:21], v[220:221], v[128:129] op_sel:[0,1,0] op_sel_hi:[1,1,1]
	v_pk_fma_f32 v[128:129], v[22:23], v[222:223], v[128:129] op_sel_hi:[1,0,1]
	v_pk_fma_f32 v[128:129], v[24:25], v[222:223], v[128:129] op_sel:[0,1,0] op_sel_hi:[1,1,1]
	v_pk_fma_f32 v[128:129], v[26:27], v[224:225], v[128:129] op_sel_hi:[1,0,1]
	v_pk_fma_f32 v[128:129], v[28:29], v[224:225], v[128:129] op_sel:[0,1,0] op_sel_hi:[1,1,1]
	v_pk_fma_f32 v[128:129], v[30:31], v[226:227], v[128:129] op_sel_hi:[1,0,1]
	v_pk_fma_f32 v[128:129], v[32:33], v[226:227], v[128:129] op_sel:[0,1,0] op_sel_hi:[1,1,1]
	v_pk_fma_f32 v[128:129], v[34:35], v[228:229], v[128:129] op_sel_hi:[1,0,1]
	v_pk_fma_f32 v[128:129], v[36:37], v[228:229], v[128:129] op_sel:[0,1,0] op_sel_hi:[1,1,1]
	v_pk_fma_f32 v[128:129], v[38:39], v[230:231], v[128:129] op_sel_hi:[1,0,1]
	v_pk_fma_f32 v[128:129], v[40:41], v[230:231], v[128:129] op_sel:[0,1,0] op_sel_hi:[1,1,1]
	ds_read_b128 v[216:219], v78 offset:768
	ds_read_b128 v[220:223], v78 offset:784
	ds_read_b128 v[224:227], v78 offset:800
	ds_read_b128 v[228:231], v78 offset:816
	v_pk_fma_f32 v[130:131], v[42:43], v[232:233], v[76:77] op_sel_hi:[1,0,1]
	v_pk_fma_f32 v[130:131], v[44:45], v[232:233], v[130:131] op_sel:[0,1,0] op_sel_hi:[1,1,1]
	v_pk_fma_f32 v[130:131], v[46:47], v[234:235], v[130:131] op_sel_hi:[1,0,1]
	v_pk_fma_f32 v[130:131], v[48:49], v[234:235], v[130:131] op_sel:[0,1,0] op_sel_hi:[1,1,1]
	v_pk_fma_f32 v[130:131], v[50:51], v[236:237], v[130:131] op_sel_hi:[1,0,1]
	v_pk_fma_f32 v[130:131], v[52:53], v[236:237], v[130:131] op_sel:[0,1,0] op_sel_hi:[1,1,1]
	v_pk_fma_f32 v[130:131], v[54:55], v[238:239], v[130:131] op_sel_hi:[1,0,1]
	v_pk_fma_f32 v[130:131], v[56:57], v[238:239], v[130:131] op_sel:[0,1,0] op_sel_hi:[1,1,1]
	v_pk_fma_f32 v[130:131], v[58:59], v[240:241], v[130:131] op_sel_hi:[1,0,1]
	v_pk_fma_f32 v[130:131], v[60:61], v[240:241], v[130:131] op_sel:[0,1,0] op_sel_hi:[1,1,1]
	v_pk_fma_f32 v[130:131], v[62:63], v[242:243], v[130:131] op_sel_hi:[1,0,1]
	v_pk_fma_f32 v[130:131], v[64:65], v[242:243], v[130:131] op_sel:[0,1,0] op_sel_hi:[1,1,1]
	v_pk_fma_f32 v[130:131], v[66:67], v[244:245], v[130:131] op_sel_hi:[1,0,1]
	v_pk_fma_f32 v[130:131], v[68:69], v[244:245], v[130:131] op_sel:[0,1,0] op_sel_hi:[1,1,1]
	v_pk_fma_f32 v[130:131], v[70:71], v[246:247], v[130:131] op_sel_hi:[1,0,1]
	v_pk_fma_f32 v[130:131], v[72:73], v[246:247], v[130:131] op_sel:[0,1,0] op_sel_hi:[1,1,1]
	ds_read_b128 v[232:235], v78 offset:832
	ds_read_b128 v[236:239], v78 offset:848
	ds_read_b128 v[240:243], v78 offset:864
	ds_read_b128 v[244:247], v78 offset:880
	v_mul_f32_e64 v132, |v128|, s33
	v_mul_f32_e64 v133, |v129|, s33
	v_mul_f32_e64 v134, |v130|, s33
	v_mul_f32_e64 v135, |v131|, s33
	v_exp_f32_e32 v132, v132
	v_exp_f32_e32 v133, v133
	v_exp_f32_e32 v134, v134
	v_exp_f32_e32 v135, v135
	v_pk_add_f32 v[132:133], v[132:133], 1.0 op_sel_hi:[1,0]
	v_pk_add_f32 v[134:135], v[134:135], 1.0 op_sel_hi:[1,0]
	v_log_f32_e32 v136, v132
	v_log_f32_e32 v137, v133
	v_log_f32_e32 v138, v134
	v_log_f32_e32 v139, v135
	v_pk_mul_f32 v[140:141], v[136:137], s[34:35] op_sel:[0,1] op_sel_hi:[1,1]
	v_pk_mul_f32 v[142:143], v[138:139], s[34:35] op_sel:[0,1] op_sel_hi:[1,1]
	v_pk_fma_f32 v[144:145], v[136:137], s[34:35], v[140:141] op_sel:[0,1,0] op_sel_hi:[1,1,1] neg_lo:[0,0,1] neg_hi:[0,0,1]
	v_pk_fma_f32 v[146:147], v[138:139], s[34:35], v[142:143] op_sel:[0,1,0] op_sel_hi:[1,1,1] neg_lo:[0,0,1] neg_hi:[0,0,1]
	v_pk_fma_f32 v[144:145], v[136:137], s[36:37], v[144:145] op_sel_hi:[1,0,1]
	v_pk_fma_f32 v[146:147], v[138:139], s[36:37], v[146:147] op_sel_hi:[1,0,1]
	v_pk_fma_f32 v[144:145], v[136:137], s[34:35], v[144:145] op_sel:[0,1,0] op_sel_hi:[1,1,1]
	v_pk_fma_f32 v[146:147], v[138:139], s[34:35], v[146:147] op_sel:[0,1,0] op_sel_hi:[1,1,1]
	v_min_f32_e32 v128, 0, v128
	v_min_f32_e32 v129, 0, v129
	v_min_f32_e32 v130, 0, v130
	v_min_f32_e32 v131, 0, v131
	v_pk_add_f32 v[128:129], v[128:129], v[144:145] neg_lo:[0,1] neg_hi:[0,1]
	v_pk_add_f32 v[130:131], v[130:131], v[146:147] neg_lo:[0,1] neg_hi:[0,1]
	v_pk_mul_f32 v[106:107], v[128:129], s[36:37] op_sel:[0,1] op_sel_hi:[1,1]
	v_pk_mul_f32 v[122:123], v[130:131], s[36:37] op_sel:[0,1] op_sel_hi:[1,1]
	s_waitcnt lgkmcnt(0)
	v_pk_fma_f32 v[128:129], v[10:11], v[216:217], v[74:75] op_sel_hi:[1,0,1]
	v_pk_fma_f32 v[128:129], v[12:13], v[216:217], v[128:129] op_sel:[0,1,0] op_sel_hi:[1,1,1]
	v_pk_fma_f32 v[128:129], v[14:15], v[218:219], v[128:129] op_sel_hi:[1,0,1]
	v_pk_fma_f32 v[128:129], v[16:17], v[218:219], v[128:129] op_sel:[0,1,0] op_sel_hi:[1,1,1]
	v_pk_fma_f32 v[128:129], v[18:19], v[220:221], v[128:129] op_sel_hi:[1,0,1]
	v_pk_fma_f32 v[128:129], v[20:21], v[220:221], v[128:129] op_sel:[0,1,0] op_sel_hi:[1,1,1]
	v_pk_fma_f32 v[128:129], v[22:23], v[222:223], v[128:129] op_sel_hi:[1,0,1]
	v_pk_fma_f32 v[128:129], v[24:25], v[222:223], v[128:129] op_sel:[0,1,0] op_sel_hi:[1,1,1]
	v_pk_fma_f32 v[128:129], v[26:27], v[224:225], v[128:129] op_sel_hi:[1,0,1]
	v_pk_fma_f32 v[128:129], v[28:29], v[224:225], v[128:129] op_sel:[0,1,0] op_sel_hi:[1,1,1]
	v_pk_fma_f32 v[128:129], v[30:31], v[226:227], v[128:129] op_sel_hi:[1,0,1]
	v_pk_fma_f32 v[128:129], v[32:33], v[226:227], v[128:129] op_sel:[0,1,0] op_sel_hi:[1,1,1]
	v_pk_fma_f32 v[128:129], v[34:35], v[228:229], v[128:129] op_sel_hi:[1,0,1]
	v_pk_fma_f32 v[128:129], v[36:37], v[228:229], v[128:129] op_sel:[0,1,0] op_sel_hi:[1,1,1]
	v_pk_fma_f32 v[128:129], v[38:39], v[230:231], v[128:129] op_sel_hi:[1,0,1]
	v_pk_fma_f32 v[128:129], v[40:41], v[230:231], v[128:129] op_sel:[0,1,0] op_sel_hi:[1,1,1]
	ds_read_b128 v[216:219], v78 offset:896
	ds_read_b128 v[220:223], v78 offset:912
	ds_read_b128 v[224:227], v78 offset:928
	ds_read_b128 v[228:231], v78 offset:944
	v_pk_fma_f32 v[130:131], v[42:43], v[232:233], v[76:77] op_sel_hi:[1,0,1]
	v_pk_fma_f32 v[130:131], v[44:45], v[232:233], v[130:131] op_sel:[0,1,0] op_sel_hi:[1,1,1]
	v_pk_fma_f32 v[130:131], v[46:47], v[234:235], v[130:131] op_sel_hi:[1,0,1]
	v_pk_fma_f32 v[130:131], v[48:49], v[234:235], v[130:131] op_sel:[0,1,0] op_sel_hi:[1,1,1]
	v_pk_fma_f32 v[130:131], v[50:51], v[236:237], v[130:131] op_sel_hi:[1,0,1]
	v_pk_fma_f32 v[130:131], v[52:53], v[236:237], v[130:131] op_sel:[0,1,0] op_sel_hi:[1,1,1]
	v_pk_fma_f32 v[130:131], v[54:55], v[238:239], v[130:131] op_sel_hi:[1,0,1]
	v_pk_fma_f32 v[130:131], v[56:57], v[238:239], v[130:131] op_sel:[0,1,0] op_sel_hi:[1,1,1]
	v_pk_fma_f32 v[130:131], v[58:59], v[240:241], v[130:131] op_sel_hi:[1,0,1]
	v_pk_fma_f32 v[130:131], v[60:61], v[240:241], v[130:131] op_sel:[0,1,0] op_sel_hi:[1,1,1]
	v_pk_fma_f32 v[130:131], v[62:63], v[242:243], v[130:131] op_sel_hi:[1,0,1]
	v_pk_fma_f32 v[130:131], v[64:65], v[242:243], v[130:131] op_sel:[0,1,0] op_sel_hi:[1,1,1]
	v_pk_fma_f32 v[130:131], v[66:67], v[244:245], v[130:131] op_sel_hi:[1,0,1]
	v_pk_fma_f32 v[130:131], v[68:69], v[244:245], v[130:131] op_sel:[0,1,0] op_sel_hi:[1,1,1]
	v_pk_fma_f32 v[130:131], v[70:71], v[246:247], v[130:131] op_sel_hi:[1,0,1]
	v_pk_fma_f32 v[130:131], v[72:73], v[246:247], v[130:131] op_sel:[0,1,0] op_sel_hi:[1,1,1]
	ds_read_b128 v[232:235], v78 offset:960
	ds_read_b128 v[236:239], v78 offset:976
	ds_read_b128 v[240:243], v78 offset:992
	ds_read_b128 v[244:247], v78 offset:1008
	v_mul_f32_e64 v132, |v128|, s33
	v_mul_f32_e64 v133, |v129|, s33
	v_mul_f32_e64 v134, |v130|, s33
	v_mul_f32_e64 v135, |v131|, s33
	v_exp_f32_e32 v132, v132
	v_exp_f32_e32 v133, v133
	v_exp_f32_e32 v134, v134
	v_exp_f32_e32 v135, v135
	v_pk_add_f32 v[132:133], v[132:133], 1.0 op_sel_hi:[1,0]
	v_pk_add_f32 v[134:135], v[134:135], 1.0 op_sel_hi:[1,0]
	v_log_f32_e32 v136, v132
	v_log_f32_e32 v137, v133
	v_log_f32_e32 v138, v134
	v_log_f32_e32 v139, v135
	v_pk_mul_f32 v[140:141], v[136:137], s[34:35] op_sel:[0,1] op_sel_hi:[1,1]
	v_pk_mul_f32 v[142:143], v[138:139], s[34:35] op_sel:[0,1] op_sel_hi:[1,1]
	v_pk_fma_f32 v[144:145], v[136:137], s[34:35], v[140:141] op_sel:[0,1,0] op_sel_hi:[1,1,1] neg_lo:[0,0,1] neg_hi:[0,0,1]
	v_pk_fma_f32 v[146:147], v[138:139], s[34:35], v[142:143] op_sel:[0,1,0] op_sel_hi:[1,1,1] neg_lo:[0,0,1] neg_hi:[0,0,1]
	v_pk_fma_f32 v[144:145], v[136:137], s[36:37], v[144:145] op_sel_hi:[1,0,1]
	v_pk_fma_f32 v[146:147], v[138:139], s[36:37], v[146:147] op_sel_hi:[1,0,1]
	v_pk_fma_f32 v[144:145], v[136:137], s[34:35], v[144:145] op_sel:[0,1,0] op_sel_hi:[1,1,1]
	v_pk_fma_f32 v[146:147], v[138:139], s[34:35], v[146:147] op_sel:[0,1,0] op_sel_hi:[1,1,1]
	v_min_f32_e32 v128, 0, v128
	v_min_f32_e32 v129, 0, v129
	v_min_f32_e32 v130, 0, v130
	v_min_f32_e32 v131, 0, v131
	v_pk_add_f32 v[128:129], v[128:129], v[144:145] neg_lo:[0,1] neg_hi:[0,1]
	v_pk_add_f32 v[130:131], v[130:131], v[146:147] neg_lo:[0,1] neg_hi:[0,1]
	v_pk_mul_f32 v[108:109], v[128:129], s[36:37] op_sel:[0,1] op_sel_hi:[1,1]
	v_pk_mul_f32 v[124:125], v[130:131], s[36:37] op_sel:[0,1] op_sel_hi:[1,1]
	s_waitcnt lgkmcnt(0)
	v_pk_fma_f32 v[128:129], v[10:11], v[216:217], v[74:75] op_sel_hi:[1,0,1]
	v_pk_fma_f32 v[128:129], v[12:13], v[216:217], v[128:129] op_sel:[0,1,0] op_sel_hi:[1,1,1]
	v_pk_fma_f32 v[128:129], v[14:15], v[218:219], v[128:129] op_sel_hi:[1,0,1]
	v_pk_fma_f32 v[128:129], v[16:17], v[218:219], v[128:129] op_sel:[0,1,0] op_sel_hi:[1,1,1]
	v_pk_fma_f32 v[128:129], v[18:19], v[220:221], v[128:129] op_sel_hi:[1,0,1]
	v_pk_fma_f32 v[128:129], v[20:21], v[220:221], v[128:129] op_sel:[0,1,0] op_sel_hi:[1,1,1]
	v_pk_fma_f32 v[128:129], v[22:23], v[222:223], v[128:129] op_sel_hi:[1,0,1]
	v_pk_fma_f32 v[128:129], v[24:25], v[222:223], v[128:129] op_sel:[0,1,0] op_sel_hi:[1,1,1]
	v_pk_fma_f32 v[128:129], v[26:27], v[224:225], v[128:129] op_sel_hi:[1,0,1]
	v_pk_fma_f32 v[128:129], v[28:29], v[224:225], v[128:129] op_sel:[0,1,0] op_sel_hi:[1,1,1]
	v_pk_fma_f32 v[128:129], v[30:31], v[226:227], v[128:129] op_sel_hi:[1,0,1]
	v_pk_fma_f32 v[128:129], v[32:33], v[226:227], v[128:129] op_sel:[0,1,0] op_sel_hi:[1,1,1]
	v_pk_fma_f32 v[128:129], v[34:35], v[228:229], v[128:129] op_sel_hi:[1,0,1]
	v_pk_fma_f32 v[128:129], v[36:37], v[228:229], v[128:129] op_sel:[0,1,0] op_sel_hi:[1,1,1]
	v_pk_fma_f32 v[128:129], v[38:39], v[230:231], v[128:129] op_sel_hi:[1,0,1]
	v_pk_fma_f32 v[128:129], v[40:41], v[230:231], v[128:129] op_sel:[0,1,0] op_sel_hi:[1,1,1]
	v_pk_fma_f32 v[130:131], v[42:43], v[232:233], v[76:77] op_sel_hi:[1,0,1]
	v_pk_fma_f32 v[130:131], v[44:45], v[232:233], v[130:131] op_sel:[0,1,0] op_sel_hi:[1,1,1]
	v_pk_fma_f32 v[130:131], v[46:47], v[234:235], v[130:131] op_sel_hi:[1,0,1]
	v_pk_fma_f32 v[130:131], v[48:49], v[234:235], v[130:131] op_sel:[0,1,0] op_sel_hi:[1,1,1]
	v_pk_fma_f32 v[130:131], v[50:51], v[236:237], v[130:131] op_sel_hi:[1,0,1]
	v_pk_fma_f32 v[130:131], v[52:53], v[236:237], v[130:131] op_sel:[0,1,0] op_sel_hi:[1,1,1]
	v_pk_fma_f32 v[130:131], v[54:55], v[238:239], v[130:131] op_sel_hi:[1,0,1]
	v_pk_fma_f32 v[130:131], v[56:57], v[238:239], v[130:131] op_sel:[0,1,0] op_sel_hi:[1,1,1]
	v_pk_fma_f32 v[130:131], v[58:59], v[240:241], v[130:131] op_sel_hi:[1,0,1]
	v_pk_fma_f32 v[130:131], v[60:61], v[240:241], v[130:131] op_sel:[0,1,0] op_sel_hi:[1,1,1]
	v_pk_fma_f32 v[130:131], v[62:63], v[242:243], v[130:131] op_sel_hi:[1,0,1]
	v_pk_fma_f32 v[130:131], v[64:65], v[242:243], v[130:131] op_sel:[0,1,0] op_sel_hi:[1,1,1]
	v_pk_fma_f32 v[130:131], v[66:67], v[244:245], v[130:131] op_sel_hi:[1,0,1]
	v_pk_fma_f32 v[130:131], v[68:69], v[244:245], v[130:131] op_sel:[0,1,0] op_sel_hi:[1,1,1]
	v_pk_fma_f32 v[130:131], v[70:71], v[246:247], v[130:131] op_sel_hi:[1,0,1]
	v_pk_fma_f32 v[130:131], v[72:73], v[246:247], v[130:131] op_sel:[0,1,0] op_sel_hi:[1,1,1]
	v_mul_f32_e64 v132, |v128|, s33
	v_mul_f32_e64 v133, |v129|, s33
	v_mul_f32_e64 v134, |v130|, s33
	v_mul_f32_e64 v135, |v131|, s33
	v_exp_f32_e32 v132, v132
	v_exp_f32_e32 v133, v133
	v_exp_f32_e32 v134, v134
	v_exp_f32_e32 v135, v135
	v_pk_add_f32 v[132:133], v[132:133], 1.0 op_sel_hi:[1,0]
	v_pk_add_f32 v[134:135], v[134:135], 1.0 op_sel_hi:[1,0]
	v_log_f32_e32 v136, v132
	v_log_f32_e32 v137, v133
	v_log_f32_e32 v138, v134
	v_log_f32_e32 v139, v135
	v_pk_mul_f32 v[140:141], v[136:137], s[34:35] op_sel:[0,1] op_sel_hi:[1,1]
	v_pk_mul_f32 v[142:143], v[138:139], s[34:35] op_sel:[0,1] op_sel_hi:[1,1]
	v_pk_fma_f32 v[144:145], v[136:137], s[34:35], v[140:141] op_sel:[0,1,0] op_sel_hi:[1,1,1] neg_lo:[0,0,1] neg_hi:[0,0,1]
	v_pk_fma_f32 v[146:147], v[138:139], s[34:35], v[142:143] op_sel:[0,1,0] op_sel_hi:[1,1,1] neg_lo:[0,0,1] neg_hi:[0,0,1]
	v_pk_fma_f32 v[144:145], v[136:137], s[36:37], v[144:145] op_sel_hi:[1,0,1]
	v_pk_fma_f32 v[146:147], v[138:139], s[36:37], v[146:147] op_sel_hi:[1,0,1]
	v_pk_fma_f32 v[144:145], v[136:137], s[34:35], v[144:145] op_sel:[0,1,0] op_sel_hi:[1,1,1]
	v_pk_fma_f32 v[146:147], v[138:139], s[34:35], v[146:147] op_sel:[0,1,0] op_sel_hi:[1,1,1]
	v_min_f32_e32 v128, 0, v128
	v_min_f32_e32 v129, 0, v129
	v_min_f32_e32 v130, 0, v130
	v_min_f32_e32 v131, 0, v131
	v_pk_add_f32 v[128:129], v[128:129], v[144:145] neg_lo:[0,1] neg_hi:[0,1]
	v_pk_add_f32 v[130:131], v[130:131], v[146:147] neg_lo:[0,1] neg_hi:[0,1]
	v_pk_mul_f32 v[110:111], v[128:129], s[36:37] op_sel:[0,1] op_sel_hi:[1,1]
	v_pk_mul_f32 v[126:127], v[130:131], s[36:37] op_sel:[0,1] op_sel_hi:[1,1]
	v_readlane_b32 s69, v251, 49
	s_nop 3
	s_add_i32 s56, s56, 64
	s_movk_i32 s51, 0x480
	s_cmpk_lt_i32 s56, 0x120
	s_cbranch_scc0 .Lp7_jdone
	s_mul_hi_u32 s57, s56, 0x71c71c8
	s_mul_i32 s51, s57, 108
	s_add_i32 s51, s51, s56
	s_and_b32 s57, s58, 3
	s_mul_i32 s57, s57, 36
	s_add_i32 s51, s51, s57
.Lp7_jdone:
	s_cmpk_lt_i32 s51, 0x480
	s_cbranch_scc0 .Lp7_no_prefetch
	s_mul_hi_u32 s80, s51, 0x1c71c72
	s_mul_i32 s92, s80, 144
	s_sub_i32 s92, s51, s92
	s_mul_hi_u32 s82, s92, 0x71c71c8
	s_mul_i32 s93, s82, 36
	s_sub_i32 s81, s92, s93
	s_lshl_b32 s92, s80, 8
	s_lshl_b32 s93, s81, 6
	s_add_i32 s92, s92, s93
	s_addk_i32 s92, 0x4000
	s_lshl_b32 s94, s80, 11
	s_add_i32 s94, s94, s93
	s_addk_i32 s94, 0xff00
	s_cmp_lt_u32 s81, 4
	s_cselect_b32 s83, s92, s94
	s_lshl_b32 s92, s32, 3
	s_add_i32 s83, s83, s92
	s_lshl_b32 s95, s82, 8
	s_mul_i32 s92, s83, 0x1800
	s_add_u32 s92, s92, s95
	s_add_u32 s84, s96, s92
	s_addc_u32 s85, s97, 0
	s_lshl_b32 s92, s83, 10
	s_add_u32 s92, s92, s95
	s_add_u32 s86, s88, 0xa27d000
	s_addc_u32 s87, s89, 0
	s_add_u32 s86, s86, s92
	s_addc_u32 s87, s87, 0
	s_add_u32 s98, s86, 0x1000000
	s_addc_u32 s99, s87, 0
	s_lshl_b32 s92, s83, 7
	s_add_u32 s100, s88, 0xf1d000
	s_addc_u32 s101, s89, 0
	s_add_u32 s100, s100, s92
	s_addc_u32 s101, s101, 0
	s_lshl_b32 s95, s82, 9
	global_load_dwordx4 v[4:7], v8, s[100:101]
	s_mov_b64 s[52:53], s[84:85]
	global_load_dword v200, v2, s[52:53] offset:1024
	s_add_u32 s52, s52, 0x1800
	s_addc_u32 s53, s53, 0
	global_load_dword v201, v2, s[52:53] offset:1024
	s_add_u32 s52, s52, 0x1800
	s_addc_u32 s53, s53, 0
	global_load_dword v202, v2, s[52:53] offset:1024
	s_add_u32 s52, s52, 0x1800
	s_addc_u32 s53, s53, 0
	global_load_dword v203, v2, s[52:53] offset:1024
	s_add_u32 s52, s52, 0x1800
	s_addc_u32 s53, s53, 0
	global_load_dword v204, v2, s[52:53] offset:1024
	s_add_u32 s52, s52, 0x1800
	s_addc_u32 s53, s53, 0
	global_load_dword v205, v2, s[52:53] offset:1024
	s_add_u32 s52, s52, 0x1800
	s_addc_u32 s53, s53, 0
	global_load_dword v206, v2, s[52:53] offset:1024
	s_add_u32 s52, s52, 0x1800
	s_addc_u32 s53, s53, 0
	global_load_dword v207, v2, s[52:53] offset:1024
	s_cmp_lt_u32 s81, 4
	s_cbranch_scc1 .Lp7_noq_load_next
	s_mov_b64 s[52:53], s[84:85]
	global_load_dword v208, v2, s[52:53]
	s_add_u32 s52, s52, 0x1800
	s_addc_u32 s53, s53, 0
	global_load_dword v209, v2, s[52:53]
	s_add_u32 s52, s52, 0x1800
	s_addc_u32 s53, s53, 0
	global_load_dword v210, v2, s[52:53]
	s_add_u32 s52, s52, 0x1800
	s_addc_u32 s53, s53, 0
	global_load_dword v211, v2, s[52:53]
	s_add_u32 s52, s52, 0x1800
	s_addc_u32 s53, s53, 0
	global_load_dword v212, v2, s[52:53]
	s_add_u32 s52, s52, 0x1800
	s_addc_u32 s53, s53, 0
	global_load_dword v213, v2, s[52:53]
	s_add_u32 s52, s52, 0x1800
	s_addc_u32 s53, s53, 0
	global_load_dword v214, v2, s[52:53]
	s_add_u32 s52, s52, 0x1800
	s_addc_u32 s53, s53, 0
	global_load_dword v215, v2, s[52:53]
